# P1 row norm and gla_c row-sum reductions: serial ds_bpermute butterfly replaced by DPP adds (lane^1,2,4,8) and v_permlane16/32_swap (lane^16,32)
# speedup vs baseline: 1.0157x; 1.0157x over previous
.LBB0_91:
	s_min_i32 s0, s8, 0x8000
	s_ashr_i32 s0, s0, 12
	s_add_i32 s5, s8, 0xffff8000
	s_ashr_i32 s9, s8, 31
	s_cmp_lt_i32 s8, 0x8000
	s_cselect_b32 s13, s9, 0
	s_cselect_b32 s12, s8, s5
	s_cselect_b32 s5, s65, s69
	s_cselect_b32 s14, s64, s68
	s_lshl_b64 s[12:13], s[12:13], 12
	s_add_u32 s16, s14, s12
	s_addc_u32 s17, s5, s13
	s_waitcnt lgkmcnt(0)
	global_load_dwordx4 v[36:39], v30, s[16:17]
	global_load_dwordx4 v[40:43], v30, s[16:17] offset:1024
	global_load_dwordx4 v[0:3], v30, s[16:17] offset:3072
	global_load_dwordx4 v[44:47], v30, s[16:17] offset:2048
	s_mul_i32 s12, s0, 0x1800
	s_ashr_i32 s13, s12, 31
	s_lshl_b64 s[12:13], s[12:13], 2
	s_add_u32 s12, s96, s12
	s_addc_u32 s13, s97, s13
	s_add_u32 s14, s12, 0x1000
	s_addc_u32 s15, s13, 0
	global_load_dwordx4 v[48:51], v30, s[14:15]
	global_load_dwordx4 v[52:55], v[22:23], off
	global_load_dwordx4 v[56:59], v30, s[12:13]
	s_lshl_b64 s[8:9], s[8:9], 11
	s_cmp_eq_u64 s[10:11], 0
	v_lshl_add_u64 v[60:61], v[20:21], 0, s[8:9]
	s_cselect_b64 s[8:9], -1, 0
	s_and_b64 vcc, s[8:9], exec
	s_cselect_b32 s9, s17, s11
	s_cselect_b32 s8, s16, s10
	s_waitcnt vmcnt(6)
	v_pk_mul_f32 v[4:5], v[38:39], v[38:39]
	v_pk_mul_f32 v[6:7], v[36:37], v[36:37]
	s_waitcnt vmcnt(5)
	v_pk_mul_f32 v[8:9], v[42:43], v[42:43]
	v_pk_mul_f32 v[10:11], v[40:41], v[40:41]
	v_pk_mov_b32 v[16:17], v[6:7], v[4:5] op_sel:[1,0]
	v_mov_b32_e32 v7, v5
	v_pk_mov_b32 v[4:5], v[10:11], v[8:9] op_sel:[1,0]
	v_mov_b32_e32 v11, v9
	s_waitcnt vmcnt(4)
	v_mul_f32_e32 v15, v0, v0
	s_waitcnt vmcnt(3)
	v_mul_f32_e32 v12, v45, v45
	v_mul_f32_e32 v14, v47, v47
	v_pk_add_f32 v[6:7], v[16:17], v[6:7]
	v_pk_add_f32 v[4:5], v[4:5], v[10:11]
	v_mul_f32_e32 v18, v1, v1
	v_mul_f32_e32 v19, v2, v2
	v_mul_f32_e32 v35, v3, v3
	v_pk_fma_f32 v[8:9], v[44:45], v[44:45], v[12:13] op_sel_hi:[1,1,0]
	v_pk_fma_f32 v[12:13], v[46:47], v[46:47], v[14:15] op_sel_hi:[1,1,0]
	v_pk_add_f32 v[6:7], v[6:7], v[6:7] op_sel:[0,1] op_sel_hi:[1,0]
	v_pk_add_f32 v[4:5], v[4:5], v[4:5] op_sel:[0,1] op_sel_hi:[1,0]
	v_mov_b32_e32 v9, v19
	v_mov_b32_e32 v13, v35
	v_mov_b32_e32 v7, v15
	v_mov_b32_e32 v5, v18
	v_pk_add_f32 v[8:9], v[8:9], v[12:13]
	v_pk_add_f32 v[4:5], v[6:7], v[4:5]
	s_waitcnt vmcnt(2)
	v_pk_add_f32 v[50:51], v[50:51], 1.0 op_sel_hi:[1,0]
	v_pk_add_f32 v[4:5], v[4:5], v[8:9]
	v_pk_add_f32 v[48:49], v[48:49], 1.0 op_sel_hi:[1,0]
	v_add_f32_e32 v4, v4, v5
	s_nop 1
	v_add_f32_dpp v4, v4, v4 quad_perm:[1,0,3,2] row_mask:0xf bank_mask:0xf
	global_load_dwordx4 v[16:19], v30, s[8:9]
	global_load_dwordx4 v[12:15], v30, s[8:9] offset:1024
	s_waitcnt lgkmcnt(0)
	s_nop 1
	v_add_f32_dpp v4, v4, v4 quad_perm:[2,3,0,1] row_mask:0xf bank_mask:0xf
	s_waitcnt lgkmcnt(0)
	s_nop 1
	v_add_f32_dpp v4, v4, v4 row_half_mirror row_mask:0xf bank_mask:0xf
	s_waitcnt lgkmcnt(0)
	s_nop 1
	v_add_f32_dpp v4, v4, v4 row_mirror row_mask:0xf bank_mask:0xf
	s_waitcnt lgkmcnt(0)
	v_mov_b32_e32 v5, v4
	s_nop 1
	v_permlane16_swap_b32_e32 v5, v4
	s_waitcnt lgkmcnt(0)
	v_add_f32_e32 v4, v4, v5
	v_mov_b32_e32 v5, v4
	s_nop 1
	v_permlane32_swap_b32_e32 v5, v4
	s_waitcnt lgkmcnt(0)
	v_add_f32_e32 v4, v4, v5
	v_fmamk_f32 v4, v4, 0x3a800000, v31
	v_rsq_f32_e32 v62, v4
	global_load_dwordx4 v[8:11], v30, s[8:9] offset:2048
	global_load_dwordx4 v[4:7], v30, s[8:9] offset:3072
	v_pk_mul_f32 v[38:39], v[38:39], v[62:63] op_sel_hi:[1,0]
	v_pk_mul_f32 v[36:37], v[36:37], v[62:63] op_sel_hi:[1,0]
	s_waitcnt vmcnt(5)
	v_pk_mul_f32 v[38:39], v[54:55], v[38:39]
	v_pk_mul_f32 v[36:37], v[52:53], v[36:37]
	s_waitcnt vmcnt(4)
	v_pk_fma_f32 v[38:39], v[50:51], v[38:39], v[58:59]
	v_pk_fma_f32 v[36:37], v[48:49], v[36:37], v[56:57]
	v_pk_mul_f32 v[42:43], v[42:43], v[62:63] op_sel_hi:[1,0]
	v_cvt_pk_bf16_f32 v36, v36, v37
	v_cvt_pk_bf16_f32 v37, v38, v39
	global_store_dwordx2 v[60:61], v[36:37], off
	global_load_dwordx4 v[36:39], v[22:23], off offset:1024
	s_nop 0
	global_load_dwordx4 v[48:51], v32, s[14:15]
	global_load_dwordx4 v[52:55], v30, s[12:13] offset:1024
	v_pk_mul_f32 v[40:41], v[40:41], v[62:63] op_sel_hi:[1,0]
	v_pk_mul_f32 v[46:47], v[46:47], v[62:63] op_sel_hi:[1,0]
	v_pk_mul_f32 v[44:45], v[44:45], v[62:63] op_sel_hi:[1,0]
	v_pk_mul_f32 v[2:3], v[2:3], v[62:63] op_sel_hi:[1,0]
	v_pk_mul_f32 v[0:1], v[0:1], v[62:63] op_sel_hi:[1,0]
	s_waitcnt vmcnt(7)
	v_mul_f32_e32 v35, v17, v17
	v_fmac_f32_e32 v35, v16, v16
	s_waitcnt vmcnt(2)
	v_pk_mul_f32 v[36:37], v[36:37], v[40:41]
	v_pk_mul_f32 v[38:39], v[38:39], v[42:43]
	s_waitcnt vmcnt(1)
	v_pk_add_f32 v[40:41], v[50:51], 1.0 op_sel_hi:[1,0]
	v_pk_add_f32 v[42:43], v[48:49], 1.0 op_sel_hi:[1,0]
	s_waitcnt vmcnt(0)
	v_pk_fma_f32 v[38:39], v[40:41], v[38:39], v[54:55]
	v_pk_fma_f32 v[36:37], v[42:43], v[36:37], v[52:53]
	v_mul_f32_e32 v52, v11, v11
	v_cvt_pk_bf16_f32 v36, v36, v37
	v_cvt_pk_bf16_f32 v37, v38, v39
	global_store_dwordx2 v[60:61], v[36:37], off offset:512
	global_load_dwordx4 v[36:39], v[22:23], off offset:2048
	s_nop 0
	global_load_dwordx4 v[40:43], v33, s[14:15]
	global_load_dwordx4 v[48:51], v30, s[12:13] offset:2048
	v_mul_f32_e32 v53, v5, v5
	v_mul_f32_e32 v54, v7, v7
	v_fmac_f32_e32 v52, v10, v10
	v_fmac_f32_e32 v53, v4, v4
	v_fmac_f32_e32 v54, v6, v6
	s_waitcnt vmcnt(2)
	v_pk_mul_f32 v[36:37], v[44:45], v[36:37]
	v_pk_mul_f32 v[38:39], v[46:47], v[38:39]
	s_waitcnt vmcnt(1)
	v_pk_add_f32 v[42:43], v[42:43], 1.0 op_sel_hi:[1,0]
	v_pk_add_f32 v[40:41], v[40:41], 1.0 op_sel_hi:[1,0]
	s_waitcnt vmcnt(0)
	v_pk_fma_f32 v[38:39], v[38:39], v[42:43], v[50:51]
	v_pk_fma_f32 v[36:37], v[36:37], v[40:41], v[48:49]
	v_mul_f32_e32 v50, v15, v15
	v_cvt_pk_bf16_f32 v36, v36, v37
	v_cvt_pk_bf16_f32 v37, v38, v39
	global_store_dwordx2 v[60:61], v[36:37], off offset:1024
	global_load_dwordx4 v[38:41], v[22:23], off offset:3072
	global_load_dwordx4 v[42:45], v34, s[14:15]
	global_load_dwordx4 v[46:49], v30, s[12:13] offset:3072
	v_mul_f32_e32 v36, v19, v19
	v_mul_f32_e32 v37, v13, v13
	v_mul_f32_e32 v51, v9, v9
	v_fmac_f32_e32 v36, v18, v18
	v_fmac_f32_e32 v37, v12, v12
	v_fmac_f32_e32 v50, v14, v14
	v_fmac_f32_e32 v51, v8, v8
	v_add_f32_e32 v35, v35, v36
	v_add_f32_e32 v36, v37, v50
	v_add_f32_e32 v37, v51, v52
	v_add_f32_e32 v35, v35, v36
	v_add_f32_e32 v50, v53, v54
	v_add_f32_e32 v35, v35, v37
	v_add_f32_e32 v35, v35, v50
	s_nop 1
	v_add_f32_dpp v35, v35, v35 quad_perm:[1,0,3,2] row_mask:0xf bank_mask:0xf
	s_waitcnt lgkmcnt(0)
	s_nop 1
	v_add_f32_dpp v35, v35, v35 quad_perm:[2,3,0,1] row_mask:0xf bank_mask:0xf
	s_waitcnt lgkmcnt(0)
	s_nop 1
	v_add_f32_dpp v35, v35, v35 row_half_mirror row_mask:0xf bank_mask:0xf
	s_waitcnt lgkmcnt(0)
	s_nop 1
	v_add_f32_dpp v35, v35, v35 row_mirror row_mask:0xf bank_mask:0xf
	s_waitcnt lgkmcnt(0)
	v_mov_b32_e32 v36, v35
	s_nop 1
	v_permlane16_swap_b32_e32 v36, v35
	s_waitcnt lgkmcnt(0)
	v_add_f32_e32 v35, v35, v36
	v_mov_b32_e32 v36, v35
	s_nop 1
	v_permlane32_swap_b32_e32 v36, v35
	s_waitcnt vmcnt(2)
	v_pk_mul_f32 v[0:1], v[0:1], v[38:39]
	v_pk_mul_f32 v[2:3], v[2:3], v[40:41]
	s_waitcnt vmcnt(1)
	v_pk_add_f32 v[38:39], v[44:45], 1.0 op_sel_hi:[1,0]
	v_pk_add_f32 v[40:41], v[42:43], 1.0 op_sel_hi:[1,0]
	s_waitcnt vmcnt(0)
	v_pk_fma_f32 v[2:3], v[2:3], v[38:39], v[48:49]
	v_pk_fma_f32 v[0:1], v[0:1], v[40:41], v[46:47]
	s_nop 0
	v_cvt_pk_bf16_f32 v0, v0, v1
	v_cvt_pk_bf16_f32 v1, v2, v3
	global_store_dwordx2 v[60:61], v[0:1], off offset:1536
	s_cbranch_vccnz .LBB0_85
	s_min_i32 s5, s4, 0x8000
	s_ashr_i32 s5, s5, 12
	s_and_b64 s[6:7], s[6:7], exec
	s_cselect_b32 s0, s5, s0
	s_mul_i32 s8, s0, 0x1800
	s_ashr_i32 s5, s4, 31
	s_ashr_i32 s9, s8, 31
	s_lshl_b64 s[6:7], s[4:5], 11
	s_lshl_b64 s[8:9], s[8:9], 2
	s_add_u32 s8, s96, s8
	s_addc_u32 s9, s97, s9
	s_add_u32 s10, s8, 0x1000
	global_load_dwordx4 v[0:3], v[22:23], off
	s_addc_u32 s11, s9, 0
	global_load_dwordx4 v[38:41], v30, s[10:11]
	global_load_dwordx4 v[42:45], v30, s[8:9]
	s_waitcnt lgkmcnt(0)
	v_add_f32_e32 v35, v35, v36
	v_fmamk_f32 v35, v35, 0x3a800000, v31
	v_rsq_f32_e32 v46, v35
	v_lshl_add_u64 v[48:49], v[20:21], 0, s[6:7]
	v_pk_mul_f32 v[18:19], v[18:19], v[46:47] op_sel_hi:[1,0]
	v_pk_mul_f32 v[16:17], v[16:17], v[46:47] op_sel_hi:[1,0]
	v_pk_mul_f32 v[14:15], v[14:15], v[46:47] op_sel_hi:[1,0]
	v_pk_mul_f32 v[12:13], v[12:13], v[46:47] op_sel_hi:[1,0]
	v_pk_mul_f32 v[10:11], v[10:11], v[46:47] op_sel_hi:[1,0]
	v_pk_mul_f32 v[8:9], v[8:9], v[46:47] op_sel_hi:[1,0]
	v_pk_mul_f32 v[6:7], v[6:7], v[46:47] op_sel_hi:[1,0]
	v_pk_mul_f32 v[4:5], v[4:5], v[46:47] op_sel_hi:[1,0]
	s_waitcnt vmcnt(2)
	v_pk_mul_f32 v[2:3], v[18:19], v[2:3]
	v_pk_mul_f32 v[0:1], v[16:17], v[0:1]
	s_waitcnt vmcnt(1)
	v_pk_add_f32 v[16:17], v[40:41], 1.0 op_sel_hi:[1,0]
	v_pk_add_f32 v[18:19], v[38:39], 1.0 op_sel_hi:[1,0]
	s_waitcnt vmcnt(0)
	v_pk_fma_f32 v[2:3], v[2:3], v[16:17], v[44:45]
	v_pk_fma_f32 v[0:1], v[0:1], v[18:19], v[42:43]
	s_nop 0
	v_cvt_pk_bf16_f32 v0, v0, v1
	v_cvt_pk_bf16_f32 v1, v2, v3
	global_store_dwordx2 v[48:49], v[0:1], off
	global_load_dwordx4 v[0:3], v[22:23], off offset:1024
	s_nop 0
	global_load_dwordx4 v[16:19], v32, s[10:11]
	global_load_dwordx4 v[36:39], v30, s[8:9] offset:1024
	s_waitcnt vmcnt(2)
	v_pk_mul_f32 v[2:3], v[14:15], v[2:3]
	v_pk_mul_f32 v[0:1], v[12:13], v[0:1]
	s_waitcnt vmcnt(1)
	v_pk_add_f32 v[12:13], v[18:19], 1.0 op_sel_hi:[1,0]
	v_pk_add_f32 v[14:15], v[16:17], 1.0 op_sel_hi:[1,0]
	s_waitcnt vmcnt(0)
	v_pk_fma_f32 v[2:3], v[2:3], v[12:13], v[38:39]
	v_pk_fma_f32 v[0:1], v[0:1], v[14:15], v[36:37]
	s_nop 0
	v_cvt_pk_bf16_f32 v0, v0, v1
	v_cvt_pk_bf16_f32 v1, v2, v3
	global_store_dwordx2 v[48:49], v[0:1], off offset:512
	global_load_dwordx4 v[0:3], v[22:23], off offset:2048
	s_nop 0
	global_load_dwordx4 v[12:15], v33, s[10:11]
	global_load_dwordx4 v[16:19], v30, s[8:9] offset:2048
	s_waitcnt vmcnt(2)
	v_pk_mul_f32 v[2:3], v[10:11], v[2:3]
	v_pk_mul_f32 v[0:1], v[8:9], v[0:1]
	s_waitcnt vmcnt(1)
	v_pk_add_f32 v[8:9], v[14:15], 1.0 op_sel_hi:[1,0]
	v_pk_add_f32 v[10:11], v[12:13], 1.0 op_sel_hi:[1,0]
	s_waitcnt vmcnt(0)
	v_pk_fma_f32 v[2:3], v[2:3], v[8:9], v[18:19]
	v_pk_fma_f32 v[0:1], v[0:1], v[10:11], v[16:17]
	s_nop 0
	v_cvt_pk_bf16_f32 v0, v0, v1
	v_cvt_pk_bf16_f32 v1, v2, v3
	global_store_dwordx2 v[48:49], v[0:1], off offset:1024
	global_load_dwordx4 v[0:3], v[22:23], off offset:3072
	s_nop 0
	global_load_dwordx4 v[8:11], v34, s[10:11]
	global_load_dwordx4 v[12:15], v30, s[8:9] offset:3072
	s_waitcnt vmcnt(2)
	v_pk_mul_f32 v[2:3], v[6:7], v[2:3]
	v_pk_mul_f32 v[0:1], v[4:5], v[0:1]
	s_waitcnt vmcnt(1)
	v_pk_add_f32 v[4:5], v[10:11], 1.0 op_sel_hi:[1,0]
	v_pk_add_f32 v[6:7], v[8:9], 1.0 op_sel_hi:[1,0]
	s_waitcnt vmcnt(0)
	v_pk_fma_f32 v[2:3], v[2:3], v[4:5], v[14:15]
	v_pk_fma_f32 v[0:1], v[0:1], v[6:7], v[12:13]
	s_nop 0
	v_cvt_pk_bf16_f32 v0, v0, v1
	v_cvt_pk_bf16_f32 v1, v2, v3
	global_store_dwordx2 v[48:49], v[0:1], off offset:1536
	s_branch .LBB0_85

.LBB0_828:
	s_or_b64 exec, exec, s[0:1]
	s_waitcnt lgkmcnt(1)
	v_lshl_add_u32 v56, v126, 2, 0
	v_add_u32_e32 v56, 0x10600, v56
	ds_write_b32 v56, v125
	s_waitcnt lgkmcnt(0)
	s_barrier
	ds_read_b32 v56, v88 offset:1024
	s_waitcnt lgkmcnt(0)
	v_cndmask_b32_e64 v57, 0, v56, s[8:9]
	v_cndmask_b32_e64 v58, 0, v56, s[10:11]
	v_cndmask_b32_e64 v57, v58, v57, s[4:5]
	v_add_f32_e32 v2, v2, v57
	v_add_f32_e32 v3, v3, v57
	v_add_f32_e32 v4, v4, v57
	v_add_f32_e32 v5, v5, v57
	v_add_f32_e32 v6, v6, v57
	v_add_f32_e32 v7, v7, v57
	v_add_f32_e32 v8, v8, v57
	v_add_f32_e32 v9, v9, v57
	v_add_f32_e32 v10, v10, v57
	v_add_f32_e32 v11, v11, v57
	v_add_f32_e32 v12, v12, v57
	v_add_f32_e32 v13, v13, v57
	ds_write2_b32 v49, v2, v3 offset0:2 offset1:131
	ds_write2_b32 v51, v4, v5 offset0:4 offset1:133
	ds_write2_b32 v53, v6, v7 offset0:6 offset1:135
	ds_write2_b32 v114, v8, v9 offset0:8 offset1:137
	ds_write2_b32 v117, v10, v11 offset0:10 offset1:139
	ds_write2_b32 v120, v12, v13 offset0:12 offset1:141
	v_add_f32_e32 v2, v0, v57
	v_add_f32_e32 v1, v1, v57
	v_add_f32_e32 v14, v14, v57
	v_add_f32_e32 v15, v15, v57
	v_add_f32_e32 v16, v16, v57
	v_add_f32_e32 v17, v17, v57
	v_add_f32_e32 v18, v18, v57
	v_add_f32_e32 v19, v19, v57
	v_add_f32_e32 v20, v20, v57
	v_add_f32_e32 v21, v21, v57
	v_add_f32_e32 v22, v22, v57
	ds_write2_b32 v112, v2, v1 offset1:129
	ds_write2_b32 v115, v14, v15 offset0:14 offset1:143
	ds_write2_b32 v118, v16, v17 offset0:16 offset1:145
	ds_write2_b32 v121, v18, v19 offset0:18 offset1:147
	ds_write2_b32 v123, v20, v21 offset0:20 offset1:149
	v_add_f32_e32 v1, v23, v57
	ds_write2_b32 v124, v22, v1 offset0:22 offset1:151
	v_add_f32_e32 v1, v24, v57
	v_add_f32_e32 v2, v25, v57
	ds_write2_b32 v122, v1, v2 offset0:24 offset1:153
	v_add_f32_e32 v1, v26, v57
	v_add_f32_e32 v2, v27, v57
	ds_write2_b32 v119, v1, v2 offset0:26 offset1:155
	v_add_f32_e32 v1, v28, v57
	v_add_f32_e32 v2, v29, v57
	ds_write2_b32 v116, v1, v2 offset0:28 offset1:157
	v_add_f32_e32 v1, v54, v57
	v_add_f32_e32 v2, v55, v57
	ds_write2_b32 v113, v1, v2 offset0:30 offset1:159
	s_and_saveexec_b64 s[0:1], s[10:11]
	v_cndmask_b32_e64 v0, v0, v56, s[4:5]
	v_cndmask_b32_e64 v1, v56, v55, s[4:5]
	v_add_f32_e32 v0, v0, v1
	ds_write_b32 v89, v0
	s_or_b64 exec, exec, s[0:1]
	v_or_b32_e32 v2, s44, v144
	v_mov_b64_e32 v[0:1], s[68:69]
	v_mad_i64_i32 v[0:1], s[0:1], v2, s79, v[0:1]
	s_lshl_b32 s70, s70, 1
	v_lshl_add_u64 v[0:1], v[0:1], 0, s[70:71]
	v_mov_b32_e32 v49, v31
	v_lshl_add_u64 v[16:17], v[0:1], 0, v[48:49]
	s_waitcnt vmcnt(0) lgkmcnt(0)
	s_barrier
	v_mov_b32_e32 v12, v150
	v_mov_b32_e32 v13, v151
	v_mov_b32_e32 v14, v152
	v_mov_b32_e32 v15, v153
	v_mov_b32_e32 v8, v154
	v_mov_b32_e32 v9, v155
	v_mov_b32_e32 v10, v156
	v_mov_b32_e32 v11, v157
	v_add_u32_e32 v0, 0x8100, v90
	v_add_u32_e32 v1, 0x8108, v90
	v_add_u32_e32 v2, 0x8110, v90
	ds_read2_b32 v[18:19], v90 offset1:1
	ds_read2_b32 v[20:21], v90 offset0:2 offset1:3
	ds_read2_b32 v[22:23], v90 offset0:4 offset1:5
	ds_read2_b32 v[24:25], v0 offset1:1
	ds_read2_b32 v[26:27], v1 offset1:1
	ds_read2_b32 v[28:29], v2 offset1:1
	v_mov_b32_e32 v4, v158
	v_mov_b32_e32 v5, v159
	v_mov_b32_e32 v6, v160
	v_mov_b32_e32 v7, v161
	v_mov_b32_e32 v0, v162
	v_mov_b32_e32 v1, v163
	v_mov_b32_e32 v2, v164
	v_mov_b32_e32 v3, v165
	s_lshl_b32 s98, s85, 3
	s_lshl_b32 s99, s86, 1
	s_or_b32 s98, s99, s98
	s_or_b32 s98, s98, 1
	s_ashr_i32 s99, s98, 31
	s_lshl_b64 s[98:99], s[98:99], 21
	s_add_u32 s98, s98, s52
	s_addc_u32 s99, s99, s53
	s_lshl_b32 s100, s45, 15
	s_add_u32 s98, s98, s100
	s_addc_u32 s99, s99, 0
	v_readlane_b32 s100, v244, 25
	v_lshrrev_b32_e32 v210, 4, v144
	v_and_b32_e32 v211, 15, v144
	v_lshl_add_u32 v210, s100, 4, v210
	v_lshlrev_b32_e32 v210, 8, v210
	v_lshl_add_u32 v210, v211, 4, v210
	global_load_dwordx4 v[150:153], v210, s[98:99]
	global_load_dwordx4 v[154:157], v210, s[98:99] offset:1024
	global_load_dwordx4 v[158:161], v210, s[98:99] offset:2048
	global_load_dwordx4 v[162:165], v210, s[98:99] offset:3072
	s_waitcnt lgkmcnt(5)
	v_mul_f32_e32 v49, 0x3fb8aa3b, v18
	v_mul_f32_e32 v51, 0xbfb8aa3b, v18
	v_mul_f32_e32 v53, 0x3fb8aa3b, v19
	v_mul_f32_e32 v54, 0xbfb8aa3b, v19
	s_waitcnt lgkmcnt(4)
	v_mul_f32_e32 v55, 0x3fb8aa3b, v20
	v_mul_f32_e32 v56, 0xbfb8aa3b, v20
	v_mul_f32_e32 v57, 0x3fb8aa3b, v21
	v_mul_f32_e32 v58, 0xbfb8aa3b, v21
	s_waitcnt lgkmcnt(3)
	v_mul_f32_e32 v59, 0x3fb8aa3b, v22
	v_mul_f32_e32 v60, 0xbfb8aa3b, v22
	v_mul_f32_e32 v61, 0x3fb8aa3b, v23
	v_mul_f32_e32 v62, 0xbfb8aa3b, v23
	s_waitcnt lgkmcnt(2)
	v_mul_f32_e32 v63, 0xbfb8aa3b, v25
	s_waitcnt lgkmcnt(1)
	v_mul_f32_e32 v64, 0x3fb8aa3b, v26
	v_mul_f32_e32 v65, 0xbfb8aa3b, v26
	v_mul_f32_e32 v66, 0x3fb8aa3b, v27
	v_mul_f32_e32 v67, 0xbfb8aa3b, v27
	v_exp_f32_e32 v18, v49
	v_exp_f32_e32 v20, v51
	v_mul_f32_e32 v49, 0x3fb8aa3b, v24
	v_mul_f32_e32 v51, 0xbfb8aa3b, v24
	v_exp_f32_e32 v19, v53
	v_exp_f32_e32 v21, v54
	v_mul_f32_e32 v53, 0x3fb8aa3b, v25
	v_exp_f32_e32 v22, v55
	v_exp_f32_e32 v24, v56
	v_exp_f32_e32 v23, v57
	v_exp_f32_e32 v25, v58
	v_exp_f32_e32 v26, v59
	v_exp_f32_e32 v54, v60
	v_exp_f32_e32 v27, v61
	v_exp_f32_e32 v55, v62
	v_exp_f32_e32 v59, v63
	v_exp_f32_e32 v60, v64
	v_exp_f32_e32 v62, v65
	v_exp_f32_e32 v61, v66
	v_exp_f32_e32 v63, v67
	s_waitcnt lgkmcnt(0)
	v_mul_f32_e32 v68, 0x3fb8aa3b, v28
	v_mul_f32_e32 v70, 0x3fb8aa3b, v29
	v_exp_f32_e32 v64, v68
	v_exp_f32_e32 v65, v70
	v_exp_f32_e32 v56, v49
	v_exp_f32_e32 v57, v53
	v_mul_f32_e32 v28, 0xbfb8aa3b, v28
	v_exp_f32_e32 v28, v28
	v_exp_f32_e32 v58, v51
	s_lshl_b32 s1, s86, 1
	s_lshl_b32 s45, s45, 15
	v_lshlrev_b32_e32 v66, 16, v12
	v_and_b32_e32 v67, 0xffff0000, v12
	v_lshlrev_b32_e32 v12, 16, v13
	v_and_b32_e32 v13, 0xffff0000, v13
	v_lshlrev_b32_e32 v68, 16, v8
	v_and_b32_e32 v69, 0xffff0000, v8
	v_lshlrev_b32_e32 v8, 16, v9
	v_and_b32_e32 v9, 0xffff0000, v9
	v_pk_mul_f32 v[66:67], v[66:67], s[74:75] op_sel_hi:[1,0]
	v_pk_mul_f32 v[12:13], v[12:13], s[74:75] op_sel_hi:[1,0]
	v_pk_mul_f32 v[62:63], v[62:63], v[8:9]
	v_pk_mul_f32 v[24:25], v[24:25], v[8:9]
	v_pk_mul_f32 v[8:9], v[66:67], v[18:19]
	v_pk_mul_f32 v[18:19], v[12:13], v[60:61]
	v_pk_mul_f32 v[12:13], v[12:13], v[22:23]
	v_lshlrev_b32_e32 v22, 16, v14
	v_and_b32_e32 v23, 0xffff0000, v14
	v_mul_f32_e32 v14, 0xbfb8aa3b, v29
	v_pk_mul_f32 v[22:23], v[22:23], s[74:75] op_sel_hi:[1,0]
	v_exp_f32_e32 v29, v14
	v_add_u32_e32 v14, 24, v90
	v_pk_mul_f32 v[60:61], v[22:23], v[64:65]
	v_pk_mul_f32 v[22:23], v[22:23], v[26:27]
	ds_read2st64_b32 v[26:27], v14 offset1:129
	v_pk_mul_f32 v[56:57], v[66:67], v[56:57]
	ds_read2st64_b32 v[66:67], v91 offset1:129
	v_lshlrev_b32_e32 v64, 16, v10
	v_and_b32_e32 v65, 0xffff0000, v10
	s_waitcnt lgkmcnt(1)
	v_mul_f32_e32 v10, 0x3fb8aa3b, v26
	v_pk_mul_f32 v[28:29], v[28:29], v[64:65]
	v_pk_mul_f32 v[54:55], v[54:55], v[64:65]
	v_exp_f32_e32 v64, v10
	v_mul_f32_e32 v10, 0xbfb8aa3b, v26
	v_exp_f32_e32 v26, v10
	v_mul_f32_e32 v10, 0x3fb8aa3b, v27
	v_pk_mul_f32 v[58:59], v[58:59], v[68:69]
	v_pk_mul_f32 v[20:21], v[20:21], v[68:69]
	v_exp_f32_e32 v68, v10
	v_mul_f32_e32 v10, 0xbfb8aa3b, v27
	v_exp_f32_e32 v14, v10
	s_waitcnt lgkmcnt(0)
	v_mul_f32_e32 v10, 0x3fb8aa3b, v66
	v_exp_f32_e32 v65, v10
	v_mul_f32_e32 v10, 0xbfb8aa3b, v66
	v_exp_f32_e32 v27, v10
	v_mul_f32_e32 v10, 0x3fb8aa3b, v67
	v_exp_f32_e32 v69, v10
	v_mul_f32_e32 v10, 0xbfb8aa3b, v67
	v_lshlrev_b32_e32 v70, 16, v15
	v_and_b32_e32 v71, 0xffff0000, v15
	v_exp_f32_e32 v15, v10
	v_pk_mul_f32 v[70:71], v[70:71], s[74:75] op_sel_hi:[1,0]
	v_lshlrev_b32_e32 v10, 16, v11
	v_pk_mul_f32 v[64:65], v[70:71], v[64:65]
	v_and_b32_e32 v11, 0xffff0000, v11
	v_pk_mul_f32 v[14:15], v[14:15], v[10:11]
	v_pk_mul_f32 v[26:27], v[26:27], v[10:11]
	v_cvt_pk_bf16_f32 v8, v8, v9
	v_cvt_pk_bf16_f32 v9, v12, v13
	v_cvt_pk_bf16_f32 v10, v22, v23
	v_cvt_pk_bf16_f32 v11, v64, v65
	v_pk_mul_f32 v[68:69], v[70:71], v[68:69]
	ds_write_b128 v92, v[8:11]
	v_cvt_pk_bf16_f32 v8, v20, v21
	v_cvt_pk_bf16_f32 v9, v24, v25
	v_cvt_pk_bf16_f32 v10, v54, v55
	v_cvt_pk_bf16_f32 v11, v26, v27
	ds_write_b128 v92, v[8:11] offset:17408
	v_cvt_pk_bf16_f32 v8, v56, v57
	v_cvt_pk_bf16_f32 v9, v18, v19
	v_cvt_pk_bf16_f32 v10, v60, v61
	v_cvt_pk_bf16_f32 v11, v68, v69
	ds_write_b128 v92, v[8:11] offset:34816
	v_cvt_pk_bf16_f32 v8, v58, v59
	v_cvt_pk_bf16_f32 v9, v62, v63
	v_cvt_pk_bf16_f32 v10, v28, v29
	v_cvt_pk_bf16_f32 v11, v14, v15
	ds_write_b128 v92, v[8:11] offset:52224
	ds_read2_b32 v[8:9], v90 offset0:64 offset1:65
	v_add_u32_e32 v10, 0x8200, v90
	ds_read2_b32 v[10:11], v10 offset1:1
	ds_read2_b32 v[12:13], v90 offset0:66 offset1:67
	ds_read2_b32 v[14:15], v90 offset0:68 offset1:69
	ds_read2_b32 v[18:19], v90 offset0:70 offset1:71
	v_add_u32_e32 v21, 0x8208, v90
	v_add_u32_e32 v24, 0x8210, v90
	v_add_u32_e32 v26, 0x8218, v90
	ds_read2_b32 v[22:23], v21 offset1:1
	ds_read2_b32 v[24:25], v24 offset1:1
	ds_read2_b32 v[26:27], v26 offset1:1
	s_waitcnt lgkmcnt(6)
	v_mul_f32_e32 v21, 0x3fb8aa3b, v10
	v_mul_f32_e32 v20, 0x3fb8aa3b, v8
	v_exp_f32_e32 v28, v21
	v_mul_f32_e32 v21, 0x3fb8aa3b, v9
	v_mul_f32_e32 v29, 0x3fb8aa3b, v11
	v_exp_f32_e32 v20, v20
	v_mul_f32_e32 v8, 0xbfb8aa3b, v8
	v_mul_f32_e32 v10, 0xbfb8aa3b, v10
	v_exp_f32_e32 v21, v21
	v_mul_f32_e32 v9, 0xbfb8aa3b, v9
	v_exp_f32_e32 v29, v29
	v_lshlrev_b32_e32 v54, 16, v4
	v_and_b32_e32 v55, 0xffff0000, v4
	v_mul_f32_e32 v4, 0xbfb8aa3b, v11
	v_exp_f32_e32 v8, v8
	v_exp_f32_e32 v10, v10
	v_exp_f32_e32 v9, v9
	v_exp_f32_e32 v11, v4
	v_pk_mul_f32 v[54:55], v[54:55], s[74:75] op_sel_hi:[1,0]
	v_lshlrev_b32_e32 v58, 16, v5
	v_pk_mul_f32 v[28:29], v[54:55], v[28:29]
	v_pk_mul_f32 v[20:21], v[54:55], v[20:21]
	v_lshlrev_b32_e32 v54, 16, v0
	v_and_b32_e32 v55, 0xffff0000, v0
	s_waitcnt lgkmcnt(5)
	v_mul_f32_e32 v0, 0x3fb8aa3b, v12
	v_pk_mul_f32 v[10:11], v[10:11], v[54:55]
	v_pk_mul_f32 v[8:9], v[8:9], v[54:55]
	v_exp_f32_e32 v54, v0
	v_mul_f32_e32 v0, 0xbfb8aa3b, v12
	v_exp_f32_e32 v12, v0
	s_waitcnt lgkmcnt(2)
	v_mul_f32_e32 v0, 0x3fb8aa3b, v22
	v_exp_f32_e32 v56, v0
	v_mul_f32_e32 v0, 0xbfb8aa3b, v22
	v_exp_f32_e32 v4, v0
	v_mul_f32_e32 v0, 0x3fb8aa3b, v13
	v_exp_f32_e32 v55, v0
	v_mul_f32_e32 v0, 0xbfb8aa3b, v13
	v_exp_f32_e32 v13, v0
	v_mul_f32_e32 v0, 0x3fb8aa3b, v23
	v_exp_f32_e32 v57, v0
	v_mul_f32_e32 v0, 0xbfb8aa3b, v23
	v_and_b32_e32 v59, 0xffff0000, v5
	v_exp_f32_e32 v5, v0
	v_lshlrev_b32_e32 v0, 16, v1
	v_and_b32_e32 v1, 0xffff0000, v1
	v_pk_mul_f32 v[12:13], v[12:13], v[0:1]
	v_pk_mul_f32 v[4:5], v[4:5], v[0:1]
	v_mul_f32_e32 v1, 0xbfb8aa3b, v14
	v_pk_mul_f32 v[58:59], v[58:59], s[74:75] op_sel_hi:[1,0]
	v_mul_f32_e32 v0, 0x3fb8aa3b, v14
	v_exp_f32_e32 v14, v1
	s_waitcnt lgkmcnt(1)
	v_mul_f32_e32 v1, 0x3fb8aa3b, v24
	v_pk_mul_f32 v[22:23], v[58:59], v[54:55]
	v_exp_f32_e32 v54, v1
	v_mul_f32_e32 v1, 0xbfb8aa3b, v24
	v_exp_f32_e32 v24, v1
	v_mul_f32_e32 v1, 0x3fb8aa3b, v15
	v_mul_f32_e32 v49, 0x3fb8aa3b, v25
	v_pk_mul_f32 v[56:57], v[58:59], v[56:57]
	v_exp_f32_e32 v0, v0
	v_exp_f32_e32 v1, v1
	v_mul_f32_e32 v15, 0xbfb8aa3b, v15
	v_exp_f32_e32 v55, v49
	v_lshlrev_b32_e32 v58, 16, v6
	v_and_b32_e32 v59, 0xffff0000, v6
	v_mul_f32_e32 v6, 0xbfb8aa3b, v25
	v_exp_f32_e32 v15, v15
	v_exp_f32_e32 v25, v6
	v_pk_mul_f32 v[58:59], v[58:59], s[74:75] op_sel_hi:[1,0]
	v_lshlrev_b32_e32 v62, 16, v7
	v_pk_mul_f32 v[54:55], v[58:59], v[54:55]
	v_pk_mul_f32 v[58:59], v[58:59], v[0:1]
	v_lshlrev_b32_e32 v0, 16, v2
	v_and_b32_e32 v1, 0xffff0000, v2
	v_pk_mul_f32 v[24:25], v[24:25], v[0:1]
	v_pk_mul_f32 v[14:15], v[14:15], v[0:1]
	v_mul_f32_e32 v1, 0xbfb8aa3b, v18
	v_mul_f32_e32 v0, 0x3fb8aa3b, v18
	v_exp_f32_e32 v18, v1
	s_waitcnt lgkmcnt(0)
	v_mul_f32_e32 v1, 0x3fb8aa3b, v26
	v_exp_f32_e32 v60, v1
	v_mul_f32_e32 v1, 0xbfb8aa3b, v26
	v_mul_f32_e32 v2, 0xbfb8aa3b, v19
	v_exp_f32_e32 v6, v1
	v_mul_f32_e32 v1, 0x3fb8aa3b, v19
	v_exp_f32_e32 v19, v2
	v_mul_f32_e32 v2, 0x3fb8aa3b, v27
	v_exp_f32_e32 v0, v0
	v_exp_f32_e32 v1, v1
	v_exp_f32_e32 v61, v2
	v_mul_f32_e32 v2, 0xbfb8aa3b, v27
	v_and_b32_e32 v63, 0xffff0000, v7
	v_exp_f32_e32 v7, v2
	v_pk_mul_f32 v[62:63], v[62:63], s[74:75] op_sel_hi:[1,0]
	v_cvt_pk_bf16_f32 v2, v58, v59
	v_pk_mul_f32 v[26:27], v[62:63], v[0:1]
	v_lshlrev_b32_e32 v0, 16, v3
	v_and_b32_e32 v1, 0xffff0000, v3
	v_pk_mul_f32 v[6:7], v[6:7], v[0:1]
	v_pk_mul_f32 v[18:19], v[18:19], v[0:1]
	v_cvt_pk_bf16_f32 v0, v20, v21
	v_cvt_pk_bf16_f32 v1, v22, v23
	v_cvt_pk_bf16_f32 v3, v26, v27
	v_pk_mul_f32 v[60:61], v[62:63], v[60:61]
	ds_write_b128 v92, v[0:3] offset:128
	v_cvt_pk_bf16_f32 v0, v8, v9
	v_cvt_pk_bf16_f32 v1, v12, v13
	v_cvt_pk_bf16_f32 v2, v14, v15
	v_cvt_pk_bf16_f32 v3, v18, v19
	ds_write_b128 v92, v[0:3] offset:17536
	v_cvt_pk_bf16_f32 v0, v28, v29
	v_cvt_pk_bf16_f32 v1, v56, v57
	v_cvt_pk_bf16_f32 v2, v54, v55
	v_cvt_pk_bf16_f32 v3, v60, v61
	ds_write_b128 v92, v[0:3] offset:34944
	v_cvt_pk_bf16_f32 v0, v10, v11
	v_cvt_pk_bf16_f32 v1, v4, v5
	v_cvt_pk_bf16_f32 v2, v24, v25
	v_cvt_pk_bf16_f32 v3, v6, v7
	ds_write_b128 v92, v[0:3] offset:52352
	s_waitcnt lgkmcnt(0)
	s_barrier
	v_mov_b32_e32 v0, v166
	v_mov_b32_e32 v1, v167
	v_mov_b32_e32 v2, v168
	v_mov_b32_e32 v3, v169
	v_mov_b32_e32 v4, v170
	v_mov_b32_e32 v5, v171
	v_mov_b32_e32 v6, v172
	v_mov_b32_e32 v7, v173
	v_readlane_b32 s99, v244, 25
	v_lshrrev_b32_e32 v210, 4, v144
	v_and_b32_e32 v211, 15, v144
	v_lshl_add_u32 v210, s99, 4, v210
	v_mul_u32_u24_e32 v210, 0x110, v210
	v_lshl_add_u32 v210, v211, 4, v210
	v_add_u32_e32 v186, 0x16c00, v210
	v_add_u32_e32 v210, 0x7000, v210
	ds_write_b128 v210, v[192:195]
	ds_write_b128 v210, v[196:199] offset:1088
	ds_write_b128 v210, v[232:235] offset:2176
	ds_write_b128 v210, v[236:239] offset:3264
	s_lshr_b32 s99, s99, 2
	s_mul_i32 s100, s99, 0x4400
	v_add_u32_e32 v186, s100, v186
	v_lshrrev_b32_e32 v211, 4, v144
	v_and_b32_e32 v210, 15, v144
	v_lshl_add_u32 v210, s99, 6, v210
	v_mul_u32_u24_e32 v210, 0x110, v210
	v_lshl_add_u32 v210, v211, 4, v210
	v_add_u32_e32 v211, 0x16c00, v210
	v_add_u32_e32 v211, s100, v211
	v_add_u32_e32 v210, 0x7000, v210
	ds_write_b16 v103, v0
	ds_write_b16_d16_hi v103, v0 offset:144
	ds_write_b16 v103, v1 offset:288
	ds_write_b16_d16_hi v103, v1 offset:432
	ds_write_b16 v103, v2 offset:576
	ds_write_b16_d16_hi v103, v2 offset:720
	ds_write_b16 v103, v3 offset:864
	ds_write_b16_d16_hi v104, v3
	ds_write_b16 v103, v4 offset:9216
	ds_write_b16_d16_hi v103, v4 offset:9360
	ds_write_b16 v103, v5 offset:9504
	ds_write_b16_d16_hi v103, v5 offset:9648
	ds_write_b16 v103, v6 offset:9792
	ds_write_b16_d16_hi v103, v6 offset:9936
	ds_write_b16 v103, v7 offset:10080
	ds_write_b16_d16_hi v103, v7 offset:10224
	ds_read_b128 v[0:3], v93
	ds_read_b128 v[4:7], v95 offset:17408
	ds_read_b128 v[8:11], v94
	ds_read_b128 v[12:15], v93 offset:64
	ds_read_b128 v[16:19], v95 offset:17472
	s_waitcnt lgkmcnt(3)
	v_mfma_f32_16x16x32_bf16 v[0:3], v[0:3], v[4:7], 0
	ds_read_b128 v[4:7], v95 offset:52224
	ds_read_b128 v[20:23], v94 offset:64
	ds_read_b128 v[24:27], v95 offset:52288
	s_waitcnt lgkmcnt(2)
	v_mfma_f32_16x16x32_bf16 v[4:7], v[8:11], v[4:7], 0
	v_mfma_f32_16x16x32_bf16 v[0:3], v[12:15], v[16:19], v[0:3]
	ds_read_b128 v[8:11], v93 offset:128
	ds_read_b128 v[12:15], v95 offset:17536
	s_waitcnt lgkmcnt(2)
	v_mfma_f32_16x16x32_bf16 v[4:7], v[20:23], v[24:27], v[4:7]
	ds_read_b128 v[16:19], v94 offset:128
	ds_read_b128 v[20:23], v93 offset:192
	ds_read_b128 v[24:27], v95 offset:17600
	s_waitcnt lgkmcnt(3)
	v_mfma_f32_16x16x32_bf16 v[0:3], v[8:11], v[12:15], v[0:3]
	ds_read_b128 v[8:11], v95 offset:52352
	ds_read_b128 v[12:15], v94 offset:192
	ds_read_b128 v[54:57], v95 offset:52416
	s_waitcnt lgkmcnt(2)
	v_mfma_f32_16x16x32_bf16 v[4:7], v[16:19], v[8:11], v[4:7]
	v_mfma_f32_16x16x32_bf16 v[0:3], v[20:23], v[24:27], v[0:3]
	s_waitcnt lgkmcnt(0)
	v_mfma_f32_16x16x32_bf16 v[4:7], v[12:15], v[54:57], v[4:7]
	s_nop 5
	v_cndmask_b32_e64 v0, v0, 0, s[12:13]
	s_nop 0
	v_cndmask_b32_e64 v4, v4, 0, s[14:15]
	v_add_f32_e32 v0, v0, v4
	v_cvt_pk_bf16_f32 v0, v0, s0
	ds_write_b16 v105, v0 offset:18432
	v_cndmask_b32_e64 v0, v1, 0, s[16:17]
	v_cndmask_b32_e64 v1, 0, v5, s[12:13]
	v_add_f32_e32 v0, v0, v1
	v_cvt_pk_bf16_f32 v0, v0, s0
	ds_write_b16 v105, v0 offset:18576
	v_cndmask_b32_e64 v0, v2, 0, s[18:19]
	v_cndmask_b32_e64 v1, v6, 0, s[20:21]
	v_add_f32_e32 v0, v0, v1
	v_cvt_pk_bf16_f32 v0, v0, s0
	ds_write_b16 v105, v0 offset:18720
	v_cndmask_b32_e64 v0, v3, 0, s[22:23]
	v_cndmask_b32_e64 v1, v7, 0, s[24:25]
	v_add_f32_e32 v0, v0, v1
	v_cvt_pk_bf16_f32 v0, v0, s0
	ds_write_b16 v105, v0 offset:18864
	ds_read_b128 v[0:3], v93
	ds_read_b128 v[4:7], v96 offset:17408
	ds_read_b128 v[8:11], v94
	ds_read_b128 v[12:15], v93 offset:64
	ds_read_b128 v[16:19], v96 offset:17472
	s_waitcnt lgkmcnt(3)
	v_mfma_f32_16x16x32_bf16 v[0:3], v[0:3], v[4:7], 0
	ds_read_b128 v[4:7], v96 offset:52224
	ds_read_b128 v[20:23], v94 offset:64
	ds_read_b128 v[24:27], v96 offset:52288
	s_waitcnt lgkmcnt(2)
	v_mfma_f32_16x16x32_bf16 v[4:7], v[8:11], v[4:7], 0
	v_mfma_f32_16x16x32_bf16 v[0:3], v[12:15], v[16:19], v[0:3]
	ds_read_b128 v[8:11], v93 offset:128
	ds_read_b128 v[12:15], v96 offset:17536
	s_waitcnt lgkmcnt(2)
	v_mfma_f32_16x16x32_bf16 v[4:7], v[20:23], v[24:27], v[4:7]
	ds_read_b128 v[16:19], v94 offset:128
	ds_read_b128 v[20:23], v93 offset:192
	ds_read_b128 v[24:27], v96 offset:17600
	s_waitcnt lgkmcnt(3)
	v_mfma_f32_16x16x32_bf16 v[0:3], v[8:11], v[12:15], v[0:3]
	ds_read_b128 v[8:11], v96 offset:52352
	ds_read_b128 v[12:15], v94 offset:192
	ds_read_b128 v[54:57], v96 offset:52416
	s_waitcnt lgkmcnt(2)
	v_mfma_f32_16x16x32_bf16 v[4:7], v[16:19], v[8:11], v[4:7]
	v_mfma_f32_16x16x32_bf16 v[0:3], v[20:23], v[24:27], v[0:3]
	s_waitcnt lgkmcnt(0)
	v_mfma_f32_16x16x32_bf16 v[4:7], v[12:15], v[54:57], v[4:7]
	s_nop 5
	v_cndmask_b32_e64 v0, v0, 0, s[26:27]
	s_nop 0
	v_cndmask_b32_e64 v4, v4, 0, s[28:29]
	v_add_f32_e32 v0, v0, v4
	v_cvt_pk_bf16_f32 v0, v0, s0
	ds_write_b16 v105, v0 offset:18464
	v_cndmask_b32_e64 v0, v1, 0, s[30:31]
	v_cndmask_b32_e64 v1, 0, v5, s[26:27]
	v_add_f32_e32 v0, v0, v1
	v_cvt_pk_bf16_f32 v0, v0, s0
	ds_write_b16 v105, v0 offset:18608
	v_cndmask_b32_e64 v0, v2, 0, s[34:35]
	v_cndmask_b32_e64 v1, v6, 0, s[36:37]
	v_add_f32_e32 v0, v0, v1
	v_cvt_pk_bf16_f32 v0, v0, s0
	ds_write_b16 v105, v0 offset:18752
	v_cndmask_b32_e64 v0, v3, 0, s[38:39]
	v_cndmask_b32_e64 v1, v7, 0, s[40:41]
	v_add_f32_e32 v0, v0, v1
	v_cvt_pk_bf16_f32 v0, v0, s0
	s_lshl_b32 s0, s85, 3
	s_or_b32 s0, s1, s0
	s_ashr_i32 s1, s0, 31
	s_lshl_b64 s[46:47], s[0:1], 21
	s_or_b32 s0, s0, 1
	s_ashr_i32 s1, s0, 31
	s_lshl_b64 s[0:1], s[0:1], 21
	s_add_u32 s48, s52, s0
	s_addc_u32 s49, s53, s1
	s_add_u32 s0, s52, s46
	s_addc_u32 s1, s53, s47
	s_add_u32 s0, s0, s45
	s_addc_u32 s1, s1, 0
	v_lshl_add_u64 v[28:29], s[0:1], 0, v[30:31]
	v_lshl_add_u64 v[24:25], v[28:29], 0, v[36:37]
	ds_write_b16 v105, v0 offset:18896
	s_waitcnt lgkmcnt(0)
	s_barrier
	s_waitcnt vmcnt(0)
	ds_write_b128 v186, v[150:153]
	ds_write_b128 v186, v[154:157] offset:1088
	ds_write_b128 v186, v[158:161] offset:2176
	ds_write_b128 v186, v[162:165] offset:3264
	ds_read_b128 v[16:19], v106 offset:18432
	ds_read_b128 v[20:23], v106 offset:18496
	ds_read_b128 v[58:61], v107
	ds_read_b128 v[74:77], v107 offset:64
	ds_read_b128 v[54:57], v98
	ds_read_b128 v[62:65], v98 offset:64
	ds_read_b128 v[66:69], v98 offset:128
	ds_read_b128 v[70:73], v98 offset:192
	ds_read_b128 v[194:197], v210
	ds_read_b128 v[198:201], v210 offset:64
	ds_read_b128 v[202:205], v210 offset:128
	ds_read_b128 v[206:209], v210 offset:192
	s_waitcnt lgkmcnt(9)
	v_mfma_f32_16x16x32_bf16 v[12:15], v[58:61], v[16:19], 0
	s_waitcnt lgkmcnt(8)
	v_mfma_f32_16x16x32_bf16 v[12:15], v[74:77], v[20:23], v[12:15]
	ds_read_b128 v[58:61], v107 offset:2304
	ds_read_b128 v[74:77], v107 offset:2368
	ds_read_b128 v[228:231], v210 offset:4352
	ds_read_b128 v[232:235], v210 offset:4416
	ds_read_b128 v[236:239], v210 offset:4480
	ds_read_b128 v[240:243], v210 offset:4544
	s_waitcnt lgkmcnt(13)
	s_waitcnt lgkmcnt(9)
	v_mfma_f32_16x16x32_bf16 v[12:15], v[194:197], v[54:57], v[12:15]
	s_waitcnt lgkmcnt(12)
	s_waitcnt lgkmcnt(8)
	v_mfma_f32_16x16x32_bf16 v[12:15], v[198:201], v[62:65], v[12:15]
	s_waitcnt lgkmcnt(11)
	s_waitcnt lgkmcnt(7)
	v_mfma_f32_16x16x32_bf16 v[12:15], v[202:205], v[66:69], v[12:15]
	s_waitcnt lgkmcnt(10)
	s_waitcnt lgkmcnt(6)
	v_mfma_f32_16x16x32_bf16 v[12:15], v[206:209], v[70:73], v[12:15]
	s_waitcnt lgkmcnt(5)
	v_mfma_f32_16x16x32_bf16 v[8:11], v[58:61], v[16:19], 0
	s_waitcnt lgkmcnt(4)
	v_mfma_f32_16x16x32_bf16 v[8:11], v[74:77], v[20:23], v[8:11]
	ds_read_b128 v[58:61], v107 offset:4608
	ds_read_b128 v[74:77], v107 offset:4672
	ds_read_b128 v[194:197], v210 offset:8704
	ds_read_b128 v[198:201], v210 offset:8768
	ds_read_b128 v[202:205], v210 offset:8832
	ds_read_b128 v[206:209], v210 offset:8896
	s_waitcnt lgkmcnt(9)
	v_mfma_f32_16x16x32_bf16 v[8:11], v[228:231], v[54:57], v[8:11]
	s_waitcnt lgkmcnt(8)
	v_mfma_f32_16x16x32_bf16 v[8:11], v[232:235], v[62:65], v[8:11]
	s_waitcnt lgkmcnt(7)
	v_mfma_f32_16x16x32_bf16 v[8:11], v[236:239], v[66:69], v[8:11]
	s_waitcnt lgkmcnt(6)
	v_mfma_f32_16x16x32_bf16 v[8:11], v[240:243], v[70:73], v[8:11]
	s_waitcnt lgkmcnt(5)
	v_mfma_f32_16x16x32_bf16 v[4:7], v[58:61], v[16:19], 0
	s_waitcnt lgkmcnt(4)
	v_mfma_f32_16x16x32_bf16 v[4:7], v[74:77], v[20:23], v[4:7]
	ds_read_b128 v[58:61], v108
	ds_read_b128 v[74:77], v108 offset:64
	ds_read_b128 v[228:231], v210 offset:13056
	ds_read_b128 v[232:235], v210 offset:13120
	ds_read_b128 v[236:239], v210 offset:13184
	ds_read_b128 v[240:243], v210 offset:13248
	s_waitcnt lgkmcnt(9)
	v_mfma_f32_16x16x32_bf16 v[4:7], v[194:197], v[54:57], v[4:7]
	s_waitcnt lgkmcnt(8)
	v_mfma_f32_16x16x32_bf16 v[4:7], v[198:201], v[62:65], v[4:7]
	s_waitcnt lgkmcnt(7)
	v_mfma_f32_16x16x32_bf16 v[4:7], v[202:205], v[66:69], v[4:7]
	s_waitcnt lgkmcnt(6)
	v_mfma_f32_16x16x32_bf16 v[4:7], v[206:209], v[70:73], v[4:7]
	s_waitcnt lgkmcnt(5)
	v_mfma_f32_16x16x32_bf16 v[0:3], v[58:61], v[16:19], 0
	s_waitcnt lgkmcnt(4)
	v_mfma_f32_16x16x32_bf16 v[0:3], v[74:77], v[20:23], v[0:3]
	ds_read_b128 v[24:27], v98 offset:34816
	ds_read_b128 v[78:81], v98 offset:34880
	ds_read_b128 v[114:117], v98 offset:34944
	ds_read_b128 v[118:121], v98 offset:35008
	s_waitcnt lgkmcnt(7)
	v_mfma_f32_16x16x32_bf16 v[0:3], v[228:231], v[54:57], v[0:3]
	s_waitcnt lgkmcnt(6)
	v_mfma_f32_16x16x32_bf16 v[0:3], v[232:235], v[62:65], v[0:3]
	s_waitcnt lgkmcnt(5)
	v_mfma_f32_16x16x32_bf16 v[0:3], v[236:239], v[66:69], v[0:3]
	s_waitcnt lgkmcnt(4)
	v_mfma_f32_16x16x32_bf16 v[0:3], v[240:243], v[70:73], v[0:3]
	s_waitcnt lgkmcnt(0)
	s_barrier
	ds_read_b128 v[194:197], v211
	ds_read_b128 v[198:201], v211 offset:64
	ds_read_b128 v[202:205], v211 offset:128
	ds_read_b128 v[206:209], v211 offset:192
	ds_read_b128 v[228:231], v211 offset:4352
	ds_read_b128 v[232:235], v211 offset:4416
	ds_read_b128 v[236:239], v211 offset:4480
	ds_read_b128 v[240:243], v211 offset:4544
	s_waitcnt lgkmcnt(7)
	v_mfma_f32_16x16x32_bf16 v[12:15], v[194:197], v[24:27], v[12:15]
	s_waitcnt lgkmcnt(6)
	v_mfma_f32_16x16x32_bf16 v[12:15], v[198:201], v[78:81], v[12:15]
	s_waitcnt lgkmcnt(5)
	v_mfma_f32_16x16x32_bf16 v[12:15], v[202:205], v[114:117], v[12:15]
	s_waitcnt lgkmcnt(4)
	v_mfma_f32_16x16x32_bf16 v[12:15], v[206:209], v[118:121], v[12:15]
	ds_read_b128 v[194:197], v211 offset:8704
	ds_read_b128 v[198:201], v211 offset:8768
	ds_read_b128 v[202:205], v211 offset:8832
	ds_read_b128 v[206:209], v211 offset:8896
	s_waitcnt lgkmcnt(7)
	v_mfma_f32_16x16x32_bf16 v[8:11], v[228:231], v[24:27], v[8:11]
	s_waitcnt lgkmcnt(6)
	v_mfma_f32_16x16x32_bf16 v[8:11], v[232:235], v[78:81], v[8:11]
	s_waitcnt lgkmcnt(5)
	v_mfma_f32_16x16x32_bf16 v[8:11], v[236:239], v[114:117], v[8:11]
	s_waitcnt lgkmcnt(4)
	v_mfma_f32_16x16x32_bf16 v[8:11], v[240:243], v[118:121], v[8:11]
	v_mul_f32_e32 v130, v13, v13
	v_mul_f32_e32 v131, v15, v15
	v_fmac_f32_e32 v130, v12, v12
	v_fmac_f32_e32 v131, v14, v14
	v_add_f32_e32 v130, v130, v131
	v_mov_b32_e32 v132, v130
	ds_read_b128 v[228:231], v211 offset:13056
	ds_read_b128 v[232:235], v211 offset:13120
	ds_read_b128 v[236:239], v211 offset:13184
	ds_read_b128 v[240:243], v211 offset:13248
	s_waitcnt lgkmcnt(7)
	v_mfma_f32_16x16x32_bf16 v[4:7], v[194:197], v[24:27], v[4:7]
	s_waitcnt lgkmcnt(6)
	v_mfma_f32_16x16x32_bf16 v[4:7], v[198:201], v[78:81], v[4:7]
	s_waitcnt lgkmcnt(5)
	v_mfma_f32_16x16x32_bf16 v[4:7], v[202:205], v[114:117], v[4:7]
	s_waitcnt lgkmcnt(4)
	v_mfma_f32_16x16x32_bf16 v[4:7], v[206:209], v[118:121], v[4:7]
	v_mul_f32_e32 v130, v9, v9
	v_mul_f32_e32 v131, v11, v11
	v_fmac_f32_e32 v130, v8, v8
	v_fmac_f32_e32 v131, v10, v10
	v_add_f32_e32 v130, v130, v131
	v_add_f32_e32 v132, v132, v130
	s_waitcnt lgkmcnt(3)
	v_mfma_f32_16x16x32_bf16 v[0:3], v[228:231], v[24:27], v[0:3]
	s_waitcnt lgkmcnt(2)
	v_mfma_f32_16x16x32_bf16 v[0:3], v[232:235], v[78:81], v[0:3]
	s_waitcnt lgkmcnt(1)
	v_mfma_f32_16x16x32_bf16 v[0:3], v[236:239], v[114:117], v[0:3]
	s_waitcnt lgkmcnt(0)
	v_mfma_f32_16x16x32_bf16 v[0:3], v[240:243], v[118:121], v[0:3]
	v_mul_f32_e32 v130, v5, v5
	v_mul_f32_e32 v131, v7, v7
	v_fmac_f32_e32 v130, v4, v4
	v_fmac_f32_e32 v131, v6, v6
	v_add_f32_e32 v130, v130, v131
	v_add_f32_e32 v132, v132, v130
	s_nop 7
	s_nop 1
	v_mul_f32_e32 v17, v1, v1
	v_mul_f32_e32 v18, v3, v3
	v_fmac_f32_e32 v17, v0, v0
	v_fmac_f32_e32 v18, v2, v2
	v_add_f32_e32 v17, v17, v18
	v_add_f32_e32 v16, v132, v17
	v_mov_b32_e32 v17, v16
	s_nop 1
	v_permlane16_swap_b32_e32 v17, v16
	s_waitcnt lgkmcnt(0)
	v_add_f32_e32 v16, v16, v17
	v_mov_b32_e32 v17, v16
	s_nop 1
	v_permlane32_swap_b32_e32 v17, v16
	s_and_saveexec_b64 s[0:1], s[42:43]
	s_cbranch_execz .LBB0_819
	s_waitcnt lgkmcnt(0)
	v_add_f32_e32 v16, v16, v17
	ds_write_b32 v99, v16 offset:27648
	s_branch .LBB0_819
